# stack12 + P0 streaming loads (w_in, x) use cache policy sc1 nt instead of nt
# speedup vs baseline: 1.0048x; 1.0048x over previous
.LBB0_25:
	s_or_b64 exec, exec, s[4:5]
	s_and_b32 s20, s17, 0x7c0
	v_cmp_lt_i32_e64 s[4:5], -1, v66
	v_or_b32_e32 v84, s20, v73
	s_waitcnt lgkmcnt(0)
	v_lshl_add_u64 v[70:71], v[66:67], 2, s[12:13]
	v_mov_b32_e32 v6, 0
	v_mov_b32_e32 v2, 0
	v_mov_b32_e32 v3, 0
	v_mov_b32_e32 v4, 0
	v_mov_b32_e32 v5, 0
	s_and_saveexec_b64 s[22:23], s[4:5]
	s_cbranch_execz .LBB0_27
	v_mul_u32_u24_e32 v2, 0x4c30, v84
	v_lshlrev_b32_e32 v66, 2, v2
	v_lshl_add_u64 v[2:3], v[70:71], 0, v[66:67]
	global_load_dwordx4 v[2:5], v[2:3], off sc1 nt
.LBB0_27:
	s_or_b64 exec, exec, s[22:23]
	v_mov_b32_e32 v7, 0
	v_mov_b32_e32 v8, 0
	v_mov_b32_e32 v9, 0
	s_and_saveexec_b64 s[22:23], s[4:5]
	s_cbranch_execz .LBB0_29
	v_mul_u32_u24_e32 v6, 0x4c30, v84
	v_lshlrev_b32_e32 v66, 2, v6
	v_lshl_add_u64 v[6:7], v[70:71], 0, v[66:67]
	v_add_co_u32_e32 v6, vcc, 0x4c000, v6
	s_nop 1
	v_addc_co_u32_e32 v7, vcc, 0, v7, vcc
	global_load_dwordx4 v[6:9], v[6:7], off offset:768 sc1 nt
.LBB0_29:
	s_or_b64 exec, exec, s[22:23]
	v_mov_b32_e32 v10, 0
	v_mov_b32_e32 v14, 0
	v_mov_b32_e32 v15, 0
	v_mov_b32_e32 v16, 0
	v_mov_b32_e32 v17, 0
	s_and_saveexec_b64 s[22:23], s[4:5]
	s_cbranch_execz .LBB0_31
	v_mul_u32_u24_e32 v11, 0x4c30, v84
	v_lshlrev_b32_e32 v66, 2, v11
	v_lshl_add_u64 v[12:13], v[70:71], 0, v[66:67]
	v_add_co_u32_e32 v12, vcc, 0x98000, v12
	s_nop 1
	v_addc_co_u32_e32 v13, vcc, 0, v13, vcc
	global_load_dwordx4 v[14:17], v[12:13], off offset:1536 sc1 nt
.LBB0_31:
	s_or_b64 exec, exec, s[22:23]
	v_mov_b32_e32 v11, 0
	v_mov_b32_e32 v12, 0
	v_mov_b32_e32 v13, 0
	s_and_saveexec_b64 s[22:23], s[4:5]
	s_cbranch_execz .LBB0_33
	v_mul_u32_u24_e32 v10, 0x4c30, v84
	v_lshlrev_b32_e32 v66, 2, v10
	v_lshl_add_u64 v[10:11], v[70:71], 0, v[66:67]
	v_add_co_u32_e32 v10, vcc, 0xe4000, v10
	s_nop 1
	v_addc_co_u32_e32 v11, vcc, 0, v11, vcc
	global_load_dwordx4 v[10:13], v[10:11], off offset:2304 sc1 nt
.LBB0_33:
	s_or_b64 exec, exec, s[22:23]
	v_mov_b32_e32 v18, 0
	v_mov_b32_e32 v22, 0
	v_mov_b32_e32 v23, 0
	v_mov_b32_e32 v24, 0
	v_mov_b32_e32 v25, 0
	s_and_saveexec_b64 s[22:23], s[4:5]
	s_cbranch_execz .LBB0_35
	v_mul_u32_u24_e32 v19, 0x4c30, v84
	v_lshlrev_b32_e32 v66, 2, v19
	v_lshl_add_u64 v[20:21], v[70:71], 0, v[66:67]
	v_add_co_u32_e32 v20, vcc, 0x130000, v20
	s_nop 1
	v_addc_co_u32_e32 v21, vcc, 0, v21, vcc
	global_load_dwordx4 v[22:25], v[20:21], off offset:3072 sc1 nt
.LBB0_35:
	s_or_b64 exec, exec, s[22:23]
	v_mov_b32_e32 v19, 0
	v_mov_b32_e32 v20, 0
	v_mov_b32_e32 v21, 0
	s_and_saveexec_b64 s[22:23], s[4:5]
	s_cbranch_execz .LBB0_37
	v_mul_u32_u24_e32 v18, 0x4c30, v84
	v_lshlrev_b32_e32 v66, 2, v18
	v_lshl_add_u64 v[18:19], v[70:71], 0, v[66:67]
	v_add_co_u32_e32 v18, vcc, 0x17c000, v18
	s_nop 1
	v_addc_co_u32_e32 v19, vcc, 0, v19, vcc
	global_load_dwordx4 v[18:21], v[18:19], off offset:3840 sc1 nt
.LBB0_37:
	s_or_b64 exec, exec, s[22:23]
	v_mov_b32_e32 v26, 0
	v_mov_b32_e32 v30, 0
	v_mov_b32_e32 v31, 0
	v_mov_b32_e32 v32, 0
	v_mov_b32_e32 v33, 0
	s_and_saveexec_b64 s[22:23], s[4:5]
	s_cbranch_execz .LBB0_39
	v_mul_u32_u24_e32 v27, 0x4c30, v84
	v_lshlrev_b32_e32 v66, 2, v27
	v_lshl_add_u64 v[28:29], v[70:71], 0, v[66:67]
	v_add_co_u32_e32 v28, vcc, 0x1c9000, v28
	s_nop 1
	v_addc_co_u32_e32 v29, vcc, 0, v29, vcc
	global_load_dwordx4 v[30:33], v[28:29], off offset:512 sc1 nt
.LBB0_39:
	s_or_b64 exec, exec, s[22:23]
	v_mov_b32_e32 v27, 0
	v_mov_b32_e32 v28, 0
	v_mov_b32_e32 v29, 0
	s_and_saveexec_b64 s[22:23], s[4:5]
	s_cbranch_execz .LBB0_41
	v_mul_u32_u24_e32 v26, 0x4c30, v84
	v_lshlrev_b32_e32 v66, 2, v26
	v_lshl_add_u64 v[26:27], v[70:71], 0, v[66:67]
	v_add_co_u32_e32 v26, vcc, 0x215000, v26
	s_nop 1
	v_addc_co_u32_e32 v27, vcc, 0, v27, vcc
	global_load_dwordx4 v[26:29], v[26:27], off offset:1280 sc1 nt
.LBB0_41:
	s_or_b64 exec, exec, s[22:23]
	v_mov_b32_e32 v34, 0
	v_mov_b32_e32 v38, 0
	v_mov_b32_e32 v39, 0
	v_mov_b32_e32 v40, 0
	v_mov_b32_e32 v41, 0
	s_and_saveexec_b64 s[22:23], s[4:5]
	s_cbranch_execz .LBB0_43
	v_mul_u32_u24_e32 v35, 0x4c30, v84
	v_lshlrev_b32_e32 v66, 2, v35
	v_lshl_add_u64 v[36:37], v[70:71], 0, v[66:67]
	v_add_co_u32_e32 v36, vcc, 0x261000, v36
	s_nop 1
	v_addc_co_u32_e32 v37, vcc, 0, v37, vcc
	global_load_dwordx4 v[38:41], v[36:37], off offset:2048 sc1 nt
.LBB0_43:
	s_or_b64 exec, exec, s[22:23]
	v_mov_b32_e32 v35, 0
	v_mov_b32_e32 v36, 0
	v_mov_b32_e32 v37, 0
	s_and_saveexec_b64 s[22:23], s[4:5]
	s_cbranch_execz .LBB0_45
	v_mul_u32_u24_e32 v34, 0x4c30, v84
	v_lshlrev_b32_e32 v66, 2, v34
	v_lshl_add_u64 v[34:35], v[70:71], 0, v[66:67]
	v_add_co_u32_e32 v34, vcc, 0x2ad000, v34
	s_nop 1
	v_addc_co_u32_e32 v35, vcc, 0, v35, vcc
	global_load_dwordx4 v[34:37], v[34:35], off offset:2816 sc1 nt
.LBB0_45:
	s_or_b64 exec, exec, s[22:23]
	v_mov_b32_e32 v42, 0
	v_mov_b32_e32 v46, 0
	v_mov_b32_e32 v47, 0
	v_mov_b32_e32 v48, 0
	v_mov_b32_e32 v49, 0
	s_and_saveexec_b64 s[22:23], s[4:5]
	s_cbranch_execz .LBB0_47
	v_mul_u32_u24_e32 v43, 0x4c30, v84
	v_lshlrev_b32_e32 v66, 2, v43
	v_lshl_add_u64 v[44:45], v[70:71], 0, v[66:67]
	v_add_co_u32_e32 v44, vcc, 0x2f9000, v44
	s_nop 1
	v_addc_co_u32_e32 v45, vcc, 0, v45, vcc
	global_load_dwordx4 v[46:49], v[44:45], off offset:3584 sc1 nt
.LBB0_47:
	s_or_b64 exec, exec, s[22:23]
	v_mov_b32_e32 v43, 0
	v_mov_b32_e32 v44, 0
	v_mov_b32_e32 v45, 0
	s_and_saveexec_b64 s[22:23], s[4:5]
	s_cbranch_execz .LBB0_49
	v_mul_u32_u24_e32 v42, 0x4c30, v84
	v_lshlrev_b32_e32 v66, 2, v42
	v_lshl_add_u64 v[42:43], v[70:71], 0, v[66:67]
	v_add_co_u32_e32 v42, vcc, 0x346000, v42
	s_nop 1
	v_addc_co_u32_e32 v43, vcc, 0, v43, vcc
	global_load_dwordx4 v[42:45], v[42:43], off offset:256 sc1 nt
.LBB0_49:
	s_or_b64 exec, exec, s[22:23]
	v_mov_b32_e32 v50, 0
	v_mov_b32_e32 v54, 0
	v_mov_b32_e32 v55, 0
	v_mov_b32_e32 v56, 0
	v_mov_b32_e32 v57, 0
	s_and_saveexec_b64 s[22:23], s[4:5]
	s_cbranch_execz .LBB0_51
	v_mul_u32_u24_e32 v51, 0x4c30, v84
	v_lshlrev_b32_e32 v66, 2, v51
	v_lshl_add_u64 v[52:53], v[70:71], 0, v[66:67]
	v_add_co_u32_e32 v52, vcc, 0x392000, v52
	s_nop 1
	v_addc_co_u32_e32 v53, vcc, 0, v53, vcc
	global_load_dwordx4 v[54:57], v[52:53], off offset:1024 sc1 nt
.LBB0_51:
	s_or_b64 exec, exec, s[22:23]
	v_mov_b32_e32 v51, 0
	v_mov_b32_e32 v52, 0
	v_mov_b32_e32 v53, 0
	s_and_saveexec_b64 s[22:23], s[4:5]
	s_cbranch_execz .LBB0_53
	v_mul_u32_u24_e32 v50, 0x4c30, v84
	v_lshlrev_b32_e32 v66, 2, v50
	v_lshl_add_u64 v[50:51], v[70:71], 0, v[66:67]
	v_add_co_u32_e32 v50, vcc, 0x3de000, v50
	s_nop 1
	v_addc_co_u32_e32 v51, vcc, 0, v51, vcc
	global_load_dwordx4 v[50:53], v[50:51], off offset:1792 sc1 nt
.LBB0_53:
	s_or_b64 exec, exec, s[22:23]
	v_mov_b32_e32 v58, 0
	v_mov_b32_e32 v62, 0
	v_mov_b32_e32 v63, 0
	v_mov_b32_e32 v64, 0
	v_mov_b32_e32 v65, 0
	s_and_saveexec_b64 s[22:23], s[4:5]
	s_cbranch_execz .LBB0_55
	v_mul_u32_u24_e32 v59, 0x4c30, v84
	v_lshlrev_b32_e32 v66, 2, v59
	v_lshl_add_u64 v[60:61], v[70:71], 0, v[66:67]
	v_add_co_u32_e32 v60, vcc, 0x42a000, v60
	s_nop 1
	v_addc_co_u32_e32 v61, vcc, 0, v61, vcc
	global_load_dwordx4 v[62:65], v[60:61], off offset:2560 sc1 nt
.LBB0_55:
	s_or_b64 exec, exec, s[22:23]
	v_mov_b32_e32 v59, 0
	v_mov_b32_e32 v60, 0
	v_mov_b32_e32 v61, 0
	s_and_saveexec_b64 s[22:23], s[4:5]
	s_cbranch_execz .LBB0_10
	v_mul_u32_u24_e32 v58, 0x4c30, v84
	v_lshlrev_b32_e32 v66, 2, v58
	v_lshl_add_u64 v[58:59], v[70:71], 0, v[66:67]
	v_add_co_u32_e32 v58, vcc, 0x476000, v58
	s_nop 1
	v_addc_co_u32_e32 v59, vcc, 0, v59, vcc
	global_load_dwordx4 v[58:61], v[58:59], off offset:3328 sc1 nt
	s_branch .LBB0_10

.LBB0_59:
	global_load_dwordx4 v[44:47], v[32:33], off offset:-4096 sc1 nt
	global_load_dwordx4 v[10:13], v[32:33], off offset:-3072 sc1 nt
	global_load_dwordx4 v[48:51], v[32:33], off offset:-2048 sc1 nt
	global_load_dwordx4 v[6:9], v[32:33], off sc1 nt
	global_load_dwordx4 v[52:55], v[32:33], off offset:-1024 sc1 nt
	global_load_dwordx4 v[18:21], v[32:33], off offset:1024 sc1 nt
	global_load_dwordx4 v[2:5], v[32:33], off offset:3072 sc1 nt
	global_load_dwordx4 v[14:17], v[32:33], off offset:2048 sc1 nt
	global_load_dwordx4 v[56:59], v[22:23], off
	s_add_i32 s16, s16, s18
	v_lshl_add_u64 v[32:33], v[32:33], 0, s[8:9]
	s_cmpk_gt_i32 s16, 0x1fff
	s_waitcnt vmcnt(8)
	v_mov_b32_e32 v62, v45
	s_waitcnt vmcnt(7)
	v_mov_b32_e32 v63, v11
	v_mov_b32_e32 v66, v47
	v_mov_b32_e32 v67, v13
	v_mov_b32_e32 v60, v44
	v_mov_b32_e32 v61, v10
	v_mov_b32_e32 v64, v46
	v_mov_b32_e32 v65, v12
	s_waitcnt vmcnt(6)
	v_pk_mul_f32 v[68:69], v[50:51], v[50:51]
	v_pk_mul_f32 v[70:71], v[48:49], v[48:49]
	v_pk_mul_f32 v[62:63], v[62:63], v[62:63]
	v_pk_mul_f32 v[66:67], v[66:67], v[66:67]
	v_pk_mov_b32 v[84:85], v[70:71], v[68:69] op_sel:[1,0]
	v_mov_b32_e32 v71, v69
	v_pk_fma_f32 v[60:61], v[60:61], v[60:61], v[62:63]
	v_pk_fma_f32 v[62:63], v[64:65], v[64:65], v[66:67]
	s_waitcnt vmcnt(4)
	v_mul_f32_e32 v72, v53, v53
	v_mul_f32_e32 v74, v55, v55
	v_pk_add_f32 v[64:65], v[84:85], v[70:71]
	v_pk_add_f32 v[60:61], v[60:61], v[62:63]
	v_mul_f32_e32 v83, v6, v6
	v_mul_f32_e32 v86, v7, v7
	v_mul_f32_e32 v87, v8, v8
	v_mul_f32_e32 v88, v9, v9
	v_pk_fma_f32 v[68:69], v[52:53], v[52:53], v[72:73] op_sel_hi:[1,1,0]
	v_pk_fma_f32 v[72:73], v[54:55], v[54:55], v[74:75] op_sel_hi:[1,1,0]
	v_pk_add_f32 v[62:63], v[64:65], v[64:65] op_sel:[0,1] op_sel_hi:[1,0]
	v_pk_add_f32 v[60:61], v[60:61], v[60:61] op_sel:[0,1] op_sel_hi:[1,0]
	s_waitcnt vmcnt(3)
	v_pk_mul_f32 v[76:77], v[20:21], v[20:21]
	v_pk_mul_f32 v[78:79], v[18:19], v[18:19]
	v_mov_b32_e32 v69, v87
	v_mov_b32_e32 v73, v88
	v_mov_b32_e32 v63, v86
	v_mov_b32_e32 v61, v83
	v_pk_mov_b32 v[74:75], v[78:79], v[76:77] op_sel:[1,0]
	v_mov_b32_e32 v79, v77
	v_pk_add_f32 v[64:65], v[68:69], v[72:73]
	v_pk_add_f32 v[60:61], v[60:61], v[62:63]
	s_waitcnt vmcnt(1)
	v_mul_f32_e32 v80, v15, v15
	v_mul_f32_e32 v82, v17, v17
	v_pk_add_f32 v[66:67], v[74:75], v[78:79]
	v_pk_add_f32 v[60:61], v[60:61], v[64:65]
	v_mul_f32_e32 v89, v2, v2
	v_mul_f32_e32 v90, v3, v3
	v_mul_f32_e32 v91, v4, v4
	v_mul_f32_e32 v92, v5, v5
	v_pk_fma_f32 v[76:77], v[14:15], v[14:15], v[80:81] op_sel_hi:[1,1,0]
	v_pk_fma_f32 v[80:81], v[16:17], v[16:17], v[82:83] op_sel_hi:[1,1,0]
	v_pk_add_f32 v[66:67], v[66:67], v[66:67] op_sel:[0,1] op_sel_hi:[1,0]
	v_pk_add_f32 v[60:61], v[60:61], v[60:61] op_sel:[0,1] op_sel_hi:[1,0]
	v_mov_b32_e32 v77, v91
	v_mov_b32_e32 v81, v92
	v_mov_b32_e32 v67, v90
	v_mov_b32_e32 v61, v89
	v_pk_add_f32 v[68:69], v[76:77], v[80:81]
	v_pk_add_f32 v[60:61], v[60:61], v[66:67]
	s_nop 0
	v_pk_add_f32 v[60:61], v[60:61], v[68:69]
	s_nop 0
	v_add_f32_e32 v60, v60, v61
	ds_bpermute_b32 v61, v36, v60
	s_waitcnt lgkmcnt(0)
	v_add_f32_e32 v60, v60, v61
	ds_bpermute_b32 v61, v37, v60
	s_waitcnt lgkmcnt(0)
	v_add_f32_e32 v60, v60, v61
	ds_bpermute_b32 v61, v38, v60
	s_waitcnt lgkmcnt(0)
	v_add_f32_e32 v60, v60, v61
	ds_bpermute_b32 v61, v39, v60
	s_waitcnt lgkmcnt(0)
	v_add_f32_e32 v60, v60, v61
	ds_bpermute_b32 v61, v40, v60
	s_waitcnt lgkmcnt(0)
	v_add_f32_e32 v60, v60, v61
	ds_bpermute_b32 v61, v41, v60
	s_waitcnt lgkmcnt(0)
	v_add_f32_e32 v60, v60, v61
	v_fmamk_f32 v60, v60, 0x3a000000, v42
	v_mul_f32_e32 v61, 0x4f800000, v60
	v_cmp_gt_f32_e32 vcc, s1, v60
	s_nop 1
	v_cndmask_b32_e32 v60, v60, v61, vcc
	v_sqrt_f32_e32 v61, v60
	s_nop 0
	v_add_u32_e32 v62, -1, v61
	v_add_u32_e32 v63, 1, v61
	v_fma_f32 v64, -v62, v61, v60
	v_fma_f32 v65, -v63, v61, v60
	v_cmp_ge_f32_e64 s[4:5], 0, v64
	s_nop 1
	v_cndmask_b32_e64 v61, v61, v62, s[4:5]
	v_cmp_lt_f32_e64 s[4:5], 0, v65
	s_nop 1
	v_cndmask_b32_e64 v61, v61, v63, s[4:5]
	v_mul_f32_e32 v62, 0x37800000, v61
	v_cndmask_b32_e32 v61, v61, v62, vcc
	v_cmp_class_f32_e32 vcc, v60, v43
	s_nop 1
	v_cndmask_b32_e32 v60, v61, v60, vcc
	v_div_scale_f32 v61, s[4:5], v60, v60, 1.0
	v_rcp_f32_e32 v63, v61
	v_div_scale_f32 v62, vcc, 1.0, v60, 1.0
	v_fma_f32 v64, -v61, v63, 1.0
	v_fmac_f32_e32 v63, v64, v63
	v_mul_f32_e32 v64, v62, v63
	v_fma_f32 v65, -v61, v64, v62
	v_fmac_f32_e32 v64, v65, v63
	v_fma_f32 v61, -v61, v64, v62
	v_div_fmas_f32 v61, v61, v63, v64
	v_div_fixup_f32 v60, v61, v60, 1.0
	v_pk_mul_f32 v[44:45], v[44:45], v[60:61] op_sel_hi:[1,0]
	v_pk_mul_f32 v[46:47], v[46:47], v[60:61] op_sel_hi:[1,0]
	s_waitcnt vmcnt(0)
	v_pk_mul_f32 v[44:45], v[56:57], v[44:45]
	v_pk_mul_f32 v[46:47], v[58:59], v[46:47]
	v_cvt_pk_bf16_f32 v44, v44, v45
	v_cvt_pk_bf16_f32 v45, v46, v47
	global_store_dwordx2 v[34:35], v[44:45], off
	global_load_dwordx4 v[44:47], v[22:23], off offset:1024
	v_pk_mul_f32 v[10:11], v[10:11], v[60:61] op_sel_hi:[1,0]
	v_pk_mul_f32 v[12:13], v[12:13], v[60:61] op_sel_hi:[1,0]
	v_pk_mul_f32 v[6:7], v[6:7], v[60:61] op_sel_hi:[1,0]
	v_pk_mul_f32 v[8:9], v[8:9], v[60:61] op_sel_hi:[1,0]
	v_pk_mul_f32 v[2:3], v[2:3], v[60:61] op_sel_hi:[1,0]
	v_pk_mul_f32 v[4:5], v[4:5], v[60:61] op_sel_hi:[1,0]
	s_waitcnt vmcnt(0)
	v_pk_mul_f32 v[10:11], v[44:45], v[10:11]
	v_pk_mul_f32 v[12:13], v[46:47], v[12:13]
	v_cvt_pk_bf16_f32 v10, v10, v11
	v_cvt_pk_bf16_f32 v11, v12, v13
	global_store_dwordx2 v[34:35], v[10:11], off offset:512
	global_load_dwordx4 v[10:13], v[22:23], off offset:2048
	v_pk_mul_f32 v[44:45], v[48:49], v[60:61] op_sel_hi:[1,0]
	v_pk_mul_f32 v[46:47], v[50:51], v[60:61] op_sel_hi:[1,0]
	s_waitcnt vmcnt(0)
	v_pk_mul_f32 v[10:11], v[10:11], v[44:45]
	v_pk_mul_f32 v[12:13], v[12:13], v[46:47]
	v_cvt_pk_bf16_f32 v10, v10, v11
	v_cvt_pk_bf16_f32 v11, v12, v13
	global_store_dwordx2 v[34:35], v[10:11], off offset:1024
	global_load_dwordx4 v[10:13], v[22:23], off offset:3072
	v_pk_mul_f32 v[44:45], v[52:53], v[60:61] op_sel_hi:[1,0]
	v_pk_mul_f32 v[46:47], v[54:55], v[60:61] op_sel_hi:[1,0]
	s_waitcnt vmcnt(0)
	v_pk_mul_f32 v[10:11], v[10:11], v[44:45]
	v_pk_mul_f32 v[12:13], v[12:13], v[46:47]
	v_cvt_pk_bf16_f32 v10, v10, v11
	v_cvt_pk_bf16_f32 v11, v12, v13
	global_store_dwordx2 v[34:35], v[10:11], off offset:1536
	global_load_dwordx4 v[10:13], v[24:25], off
	s_waitcnt vmcnt(0)
	v_pk_mul_f32 v[6:7], v[6:7], v[10:11]
	v_pk_mul_f32 v[8:9], v[8:9], v[12:13]
	v_cvt_pk_bf16_f32 v6, v6, v7
	v_cvt_pk_bf16_f32 v7, v8, v9
	global_store_dwordx2 v[34:35], v[6:7], off offset:2048
	global_load_dwordx4 v[6:9], v[26:27], off
	v_pk_mul_f32 v[10:11], v[18:19], v[60:61] op_sel_hi:[1,0]
	v_pk_mul_f32 v[12:13], v[20:21], v[60:61] op_sel_hi:[1,0]
	s_waitcnt vmcnt(0)
	v_pk_mul_f32 v[6:7], v[10:11], v[6:7]
	v_pk_mul_f32 v[8:9], v[12:13], v[8:9]
	v_cvt_pk_bf16_f32 v6, v6, v7
	v_cvt_pk_bf16_f32 v7, v8, v9
	global_store_dwordx2 v[34:35], v[6:7], off offset:2560
	global_load_dwordx4 v[6:9], v[28:29], off
	v_pk_mul_f32 v[10:11], v[14:15], v[60:61] op_sel_hi:[1,0]
	v_pk_mul_f32 v[12:13], v[16:17], v[60:61] op_sel_hi:[1,0]
	s_waitcnt vmcnt(0)
	v_pk_mul_f32 v[6:7], v[10:11], v[6:7]
	v_pk_mul_f32 v[8:9], v[12:13], v[8:9]
	v_cvt_pk_bf16_f32 v6, v6, v7
	v_cvt_pk_bf16_f32 v7, v8, v9
	global_store_dwordx2 v[34:35], v[6:7], off offset:3072
	global_load_dwordx4 v[6:9], v[30:31], off
	s_waitcnt vmcnt(0)
	v_pk_mul_f32 v[2:3], v[2:3], v[6:7]
	v_pk_mul_f32 v[4:5], v[4:5], v[8:9]
	v_cvt_pk_bf16_f32 v2, v2, v3
	v_cvt_pk_bf16_f32 v3, v4, v5
	global_store_dwordx2 v[34:35], v[2:3], off offset:3584
	v_lshl_add_u64 v[34:35], v[34:35], 0, s[10:11]
	s_cbranch_scc0 .LBB0_59
